# row-phase k=6 prologue (loop 56): sc loads renamed to free regs, intermediate vmcnt waits removed, pk_adds batched before loop
# speedup vs baseline: 1.0112x; 1.0112x over previous
.LBB0_51:
	s_and_b64 vcc, exec, s[2:3]
	s_mov_b64 s[46:47], 0
	s_cbranch_vccz .LBB0_62
	s_mov_b64 s[2:3], -1
	s_mov_b64 s[82:83], 0
	s_cmp_gt_i32 s71, 5
	s_cbranch_scc0 .LBB0_59
	s_cmp_eq_u32 s71, 6
	s_mov_b64 s[46:47], -1
	s_cbranch_scc0 .LBB0_58
	v_mov_b32_e32 v64, v135
	s_mov_b64 s[2:3], s[0:1]
	s_mov_b64 s[2:3], s[0:1]
	s_mov_b64 s[4:5], s[0:1]
	s_mov_b64 s[6:7], s[0:1]
	s_mov_b64 s[6:7], s[0:1]
	s_lshl_b32 s6, s19, 3
	s_abs_i32 s6, s6
	s_waitcnt vmcnt(5)
	v_cvt_f32_u32_e32 v0, s6
	s_sub_i32 s8, 0, s6
	s_bfe_i32 s7, s19, 0x1001c
	v_rcp_iflag_f32_e32 v0, v0
	s_nop 0
	v_mul_f32_e32 v0, 0x4f7ffffe, v0
	v_cvt_u32_f32_e32 v0, v0
	s_nop 0
	v_readfirstlane_b32 s9, v0
	s_mul_i32 s8, s8, s9
	s_mul_hi_u32 s8, s9, s8
	s_add_i32 s9, s9, s8
	s_lshr_b32 s8, s9, 18
	s_mul_i32 s9, s8, s6
	s_sub_i32 s9, 0x4000, s9
	s_add_i32 s10, s8, 1
	s_sub_i32 s11, s9, s6
	s_cmp_ge_u32 s9, s6
	s_cselect_b32 s8, s10, s8
	s_cselect_b32 s9, s11, s9
	s_add_i32 s10, s8, 1
	s_cmp_ge_u32 s9, s6
	s_cselect_b32 s6, s10, s8
	s_xor_b32 s6, s6, s7
	s_sub_i32 s6, s6, s7
	s_cmp_lt_i32 s6, 1
	s_cbranch_scc1 .LBB0_57
	v_ashrrev_i32_e32 v0, 6, v64
	v_readlane_b32 s7, v254, 3
	s_load_dwordx2 s[2:3], s[2:3], 0x88
	s_nop 0
	s_load_dwordx2 s[4:5], s[4:5], 0x40
	v_add_u32_e32 v0, s7, v0
	v_mul_lo_u32 v72, s6, v0
	v_add_u32_e32 v0, 0xffffe000, v72
	v_ashrrev_i32_e32 v0, 11, v0
	s_movk_i32 s7, 0x1fff
	v_add_u32_e32 v0, 1, v0
	v_cmp_lt_i32_e32 vcc, s7, v72
	s_waitcnt lgkmcnt(0)
	v_mov_b64_e32 v[2:3], s[2:3]
	s_mul_i32 s7, s40, 0x1800
	v_cndmask_b32_e32 v0, 0, v0, vcc
	v_mad_u64_u32 v[0:1], s[8:9], s40, 5, v[0:1]
	v_mad_i64_i32 v[32:33], s[8:9], v0, s90, v[2:3]
	s_mov_b64 s[8:9], 0x6245000
	s_nop 0
	v_lshl_add_u64 v[16:17], v[32:33], 0, s[8:9]
	s_add_i32 s8, s7, 0x800
	s_ashr_i32 s9, s8, 31
	s_lshl_b64 s[8:9], s[8:9], 2
	v_lshlrev_b32_e32 v0, 3, v64
	s_add_u32 s8, s4, s8
	v_and_b32_e32 v65, 0x1f8, v0
	s_addc_u32 s9, s5, s9
	v_lshlrev_b32_e32 v132, 2, v65
	s_add_u32 s8, s8, 0x1000
	s_waitcnt vmcnt(2)
	v_or_b32_e32 v56, 0x800, v132
	v_mov_b32_e32 v57, v133
	s_addc_u32 s9, s9, 0
	v_lshl_add_u64 v[4:5], v[16:17], 0, v[132:133]
	v_lshl_add_u64 v[20:21], v[16:17], 0, v[56:57]
	global_load_dwordx4 v[0:3], v[4:5], off offset:16
	s_nop 0
	global_load_dwordx4 v[4:7], v[4:5], off
	s_nop 0
	global_load_dwordx4 v[8:11], v132, s[8:9] offset:16
	global_load_dwordx4 v[12:15], v132, s[8:9]
	global_load_dwordx4 v[16:19], v[20:21], off offset:16
	s_nop 0
	global_load_dwordx4 v[20:23], v[20:21], off
	s_nop 0
	global_load_dwordx4 v[24:27], v56, s[8:9] offset:16
	global_load_dwordx4 v[28:31], v56, s[8:9]
	s_mov_b64 s[8:9], 0x6246000
	v_lshl_add_u64 v[52:53], v[32:33], 0, s[8:9]
	s_mov_b64 s[8:9], 0x6247000
	v_lshl_add_u64 v[58:59], v[32:33], 0, s[8:9]
	v_lshl_add_u64 v[36:37], v[52:53], 0, v[132:133]
	s_waitcnt vmcnt(9)
	v_lshl_add_u64 v[40:41], v[58:59], 0, v[132:133]
	global_load_dwordx4 v[32:35], v[36:37], off offset:16
	s_nop 0
	global_load_dwordx4 v[36:39], v[36:37], off
	s_nop 0
	global_load_dwordx4 v[216:219], v[40:41], off offset:16
	s_nop 0
	global_load_dwordx4 v[220:223], v[40:41], off
	s_add_i32 s58, s7, 0x1000
	s_lshl_b64 s[8:9], s[58:59], 2
	s_add_u32 s4, s4, s8
	s_addc_u32 s5, s5, s9
	v_lshl_add_u64 v[52:53], v[52:53], 0, v[56:57]
	v_lshl_add_u64 v[56:57], v[58:59], 0, v[56:57]
	v_ashrrev_i32_e32 v73, 31, v72
	v_and_b32_e32 v64, 63, v64
	global_load_dwordx4 v[40:43], v132, s[4:5] offset:16
	global_load_dwordx4 v[44:47], v132, s[4:5]
	global_load_dwordx4 v[48:51], v[52:53], off offset:16
	s_nop 0
	global_load_dwordx4 v[52:55], v[52:53], off
	s_nop 0
	global_load_dwordx4 v[224:227], v[56:57], off offset:16
	s_nop 0
	global_load_dwordx4 v[228:231], v[56:57], off
	global_load_dwordx4 v[56:59], v132, s[4:5] offset:2064
	global_load_dwordx4 v[60:63], v132, s[4:5] offset:2048
	s_add_u32 s4, s2, 0x62a4400
	v_lshlrev_b32_e32 v132, 1, v65
	s_addc_u32 s5, s3, 0
	v_lshl_add_u64 v[66:67], s[2:3], 0, v[132:133]
	s_mov_b64 s[2:3], 0x82a4400
	v_lshl_add_u64 v[90:91], v[66:67], 0, s[2:3]
	v_lshlrev_b64 v[66:67], 11, v[72:73]
	v_lshl_or_b32 v66, v64, 4, v66
	v_lshl_add_u64 v[92:93], s[4:5], 0, v[132:133]
	v_lshl_add_u64 v[94:95], s[4:5], 0, v[66:67]
	s_mov_b64 s[2:3], 0
	s_waitcnt vmcnt(2)
	v_pk_add_f32 v[78:79], v[218:219], 1.0 op_sel_hi:[1,0]
	v_pk_add_f32 v[74:75], v[222:223], 1.0 op_sel_hi:[1,0]
	v_pk_add_f32 v[76:77], v[220:221], 1.0 op_sel_hi:[1,0]
	v_pk_add_f32 v[80:81], v[216:217], 1.0 op_sel_hi:[1,0]
	v_pk_add_f32 v[88:89], v[224:225], 1.0 op_sel_hi:[1,0]
	v_pk_add_f32 v[82:83], v[230:231], 1.0 op_sel_hi:[1,0]
	v_pk_add_f32 v[84:85], v[228:229], 1.0 op_sel_hi:[1,0]
	v_pk_add_f32 v[86:87], v[226:227], 1.0 op_sel_hi:[1,0]
